# GEMM rope epilogue (QKV_B q|k jobs): all 16 cos/sin loads issued up front with one counted vmcnt per row group, scalar fma rope math in place (no packed fp32), 32-bit store offsets
# baseline (speedup 1.0000x reference)
;     __device__ __forceinline__ void operator()(const f32x4 (&acc)[2][2][4][2], const Unit& u, int wr, int wc, int fr, int fq) const {
;         const int row0 = u.pm * BM + wr * 64 + fr, col0 = u.pn * BM + wc * 32 + 8 * fq;
;         if (dry) return;
;         if (mode == 3) {
;     ...
;             for (int m = 0; m < 4; ++m) {
;                 const int row = row0 + ai * HALF + m * 16;
;                 bf16_t* rowp = O + (size_t)row * ldc + col0;
;                 f32x4 cs0 = {1.f, 0.f, 1.f, 0.f}, cs1 = {1.f, 0.f, 1.f, 0.f};
;                 if (mode == 1) {
;                     const int L1 = (1 << log2L) - 1, line = row >> log2L, uu = row & L1, rho = line & ((1 << log2d) - 1), pos = (uu << log2d) + rho;
;                     const float* tp = rope + ((size_t)pos * 32 + (wc & 1) * 16 + 4 * fq) * 2;
;                     cs0 = *(const f32x4*)tp; cs1 = *(const f32x4*)(tp + 4);
.LBB0_121:
	s_andn2_b64 vcc, exec, s[54:55]
	s_cbranch_vccnz .LBB0_256
	s_lshl_b32 s66, s89, 8
	v_add_u32_e32 v209, s66, v180
	v_lshl_or_b32 v146, s57, 8, v207
	s_cmp_eq_u32 s60, 2
	s_cbranch_scc1 .Lmy_epi_relu
	s_cmp_eq_u32 s60, 1
	s_cbranch_scc1 .Lmy_epi_rope
	s_cmp_eq_u32 s60, 0
	s_cbranch_scc1 .Lmy_epi_plain
	s_andn2_b64 vcc, exec, s[34:35]
	s_mov_b64 s[8:9], -1
	s_cbranch_vccnz .LBB0_252
	s_and_b64 vcc, exec, s[30:31]
	s_cbranch_vccz .LBB0_125
	v_ashrrev_i32_e32 v96, s10, v209
	v_and_b32_e32 v130, s28, v209
	v_and_b32_e32 v96, s88, v96
	v_lshl_add_u32 v96, v130, s53, v96
	v_lshlrev_b64 v[130:131], 8, v[96:97]
	v_lshl_add_u64 v[130:131], v[162:163], 0, v[130:131]
	global_load_dwordx4 v[134:137], v[130:131], off
	s_nop 0
	global_load_dwordx4 v[130:133], v[130:131], off offset:16
	s_cmp_lt_i32 s60, 2
	s_cbranch_scc1 .LBB0_129
	s_branch .LBB0_126

; __device__ __forceinline__ unsigned cvt_pk_bf16(float lo, float hi) { unsigned r; asm volatile("v_cvt_pk_bf16_f32 %0, %1, %2" : "=v"(r) : "v"(lo), "v"(hi)); return r; }
;     __device__ __forceinline__ void operator()(const f32x4 (&acc)[2][2][4][2], const Unit& u, int wr, int wc, int fr, int fq) const {
;     ...
;                 const int row = row0 + ai * HALF + m * 16;
;                 bf16_t* rowp = O + (size_t)row * ldc + col0;
;                 f32x4 cs0 = {1.f, 0.f, 1.f, 0.f}, cs1 = {1.f, 0.f, 1.f, 0.f};
;                 if (mode == 1) {
;                     const int L1 = (1 << log2L) - 1, line = row >> log2L, uu = row & L1, rho = line & ((1 << log2d) - 1), pos = (uu << log2d) + rho;
;                     const float* tp = rope + ((size_t)pos * 32 + (wc & 1) * 16 + 4 * fq) * 2;
;                     cs0 = *(const f32x4*)tp; cs1 = *(const f32x4*)(tp + 4);
;                 }
; #pragma unroll
;                 for (int bj = 0; bj < 2; ++bj) {
;                     f32x4 v0 = acc[ai][bj][m][0], v1 = acc[ai][bj][m][1];
;                     if (mode == 2) {
; #pragma unroll
;                         for (int e = 0; e < 4; ++e) { float a = fmaxf(v0[e], 0.f), b = fmaxf(v1[e], 0.f); v0[e] = a * a; v1[e] = b * b; }
;                     } else if (mode == 1) {
;                         f32x4 r0, r1;
;                         r0[0] = v0[0] * cs0[0] - v0[1] * cs0[1]; r0[1] = v0[0] * cs0[1] + v0[1] * cs0[0];
;                         r0[2] = v0[2] * cs0[2] - v0[3] * cs0[3]; r0[3] = v0[2] * cs0[3] + v0[3] * cs0[2];
;                         r1[0] = v1[0] * cs1[0] - v1[1] * cs1[1]; r1[1] = v1[0] * cs1[1] + v1[1] * cs1[0];
;                         r1[2] = v1[2] * cs1[2] - v1[3] * cs1[3]; r1[3] = v1[2] * cs1[3] + v1[3] * cs1[2];
;                         v0 = r0; v1 = r1;
;                     }
;                     u32x4 w; w.x = cvt_pk_bf16(v0[0], v0[1]); w.y = cvt_pk_bf16(v0[2], v0[3]); w.z = cvt_pk_bf16(v1[0], v1[1]); w.w = cvt_pk_bf16(v1[2], v1[3]);
;                     *(u32x4*)(rowp + bj * HALF) = w;
.Lmy_epi_rope:
	v_mov_b32_e32 v250, v209
	v_ashrrev_i32_e32 v96, s10, v250
	v_and_b32_e32 v130, s28, v250
	v_and_b32_e32 v96, s88, v96
	v_lshl_add_u32 v96, v130, s53, v96
	v_lshlrev_b64 v[130:131], 8, v[96:97]
	v_lshl_add_u64 v[130:131], v[162:163], 0, v[130:131]
	global_load_dwordx4 v[132:135], v[130:131], off
	global_load_dwordx4 v[136:139], v[130:131], off offset:16
	v_add_u32_e32 v250, 16, v209
	v_ashrrev_i32_e32 v96, s10, v250
	v_and_b32_e32 v130, s28, v250
	v_and_b32_e32 v96, s88, v96
	v_lshl_add_u32 v96, v130, s53, v96
	v_lshlrev_b64 v[130:131], 8, v[96:97]
	v_lshl_add_u64 v[130:131], v[162:163], 0, v[130:131]
	global_load_dwordx4 v[140:143], v[130:131], off
	global_load_dwordx4 v[148:151], v[130:131], off offset:16
	v_add_u32_e32 v250, 32, v209
	v_ashrrev_i32_e32 v96, s10, v250
	v_and_b32_e32 v130, s28, v250
	v_and_b32_e32 v96, s88, v96
	v_lshl_add_u32 v96, v130, s53, v96
	v_lshlrev_b64 v[130:131], 8, v[96:97]
	v_lshl_add_u64 v[130:131], v[162:163], 0, v[130:131]
	global_load_dwordx4 v[168:171], v[130:131], off
	global_load_dwordx4 v[172:175], v[130:131], off offset:16
	v_add_u32_e32 v250, 48, v209
	v_ashrrev_i32_e32 v96, s10, v250
	v_and_b32_e32 v130, s28, v250
	v_and_b32_e32 v96, s88, v96
	v_lshl_add_u32 v96, v130, s53, v96
	v_lshlrev_b64 v[130:131], 8, v[96:97]
	v_lshl_add_u64 v[130:131], v[162:163], 0, v[130:131]
	global_load_dwordx4 v[176:179], v[130:131], off
	global_load_dwordx4 v[210:213], v[130:131], off offset:16
	v_add_u32_e32 v250, 128, v209
	v_ashrrev_i32_e32 v96, s10, v250
	v_and_b32_e32 v130, s28, v250
	v_and_b32_e32 v96, s88, v96
	v_lshl_add_u32 v96, v130, s53, v96
	v_lshlrev_b64 v[130:131], 8, v[96:97]
	v_lshl_add_u64 v[130:131], v[162:163], 0, v[130:131]
	global_load_dwordx4 v[214:217], v[130:131], off
	global_load_dwordx4 v[218:221], v[130:131], off offset:16
	v_add_u32_e32 v250, 144, v209
	v_ashrrev_i32_e32 v96, s10, v250
	v_and_b32_e32 v130, s28, v250
	v_and_b32_e32 v96, s88, v96
	v_lshl_add_u32 v96, v130, s53, v96
	v_lshlrev_b64 v[130:131], 8, v[96:97]
	v_lshl_add_u64 v[130:131], v[162:163], 0, v[130:131]
	global_load_dwordx4 v[222:225], v[130:131], off
	global_load_dwordx4 v[226:229], v[130:131], off offset:16
	v_add_u32_e32 v250, 160, v209
	v_ashrrev_i32_e32 v96, s10, v250
	v_and_b32_e32 v130, s28, v250
	v_and_b32_e32 v96, s88, v96
	v_lshl_add_u32 v96, v130, s53, v96
	v_lshlrev_b64 v[130:131], 8, v[96:97]
	v_lshl_add_u64 v[130:131], v[162:163], 0, v[130:131]
	global_load_dwordx4 v[230:233], v[130:131], off
	global_load_dwordx4 v[234:237], v[130:131], off offset:16
	v_add_u32_e32 v250, 176, v209
	v_ashrrev_i32_e32 v96, s10, v250
	v_and_b32_e32 v130, s28, v250
	v_and_b32_e32 v96, s88, v96
	v_lshl_add_u32 v96, v130, s53, v96
	v_lshlrev_b64 v[130:131], 8, v[96:97]
	v_lshl_add_u64 v[130:131], v[162:163], 0, v[130:131]
	global_load_dwordx4 v[238:241], v[130:131], off
	global_load_dwordx4 v[242:245], v[130:131], off offset:16
	v_mul_lo_u32 v250, v209, s38
	s_lshl_b32 s8, s38, 5
	s_mul_i32 s9, s38, 0xa0
	v_add_lshl_u32 v251, v250, v146, 1
	s_waitcnt vmcnt(14)
	v_mul_f32_e32 v96, v127, v133
	v_mul_f32_e32 v250, v127, v132
	v_mul_f32_e32 v130, v126, v132
	v_fma_f32 v127, v126, v133, v250
	v_sub_f32_e32 v126, v130, v96
	v_mul_f32_e32 v96, v129, v135
	v_mul_f32_e32 v250, v129, v134
	v_fma_f32 v129, v128, v135, v250
	v_fma_f32 v128, v128, v134, -v96
	v_mul_f32_e32 v96, v123, v137
	v_mul_f32_e32 v250, v123, v136
	v_mul_f32_e32 v130, v122, v136
	v_fma_f32 v123, v122, v137, v250
	v_sub_f32_e32 v122, v130, v96
	v_mul_f32_e32 v96, v125, v139
	v_mul_f32_e32 v250, v125, v138
	v_fma_f32 v125, v124, v139, v250
	v_fma_f32 v124, v124, v138, -v96
	v_cvt_pk_bf16_f32 v246, v126, v127
	v_cvt_pk_bf16_f32 v247, v128, v129
	v_cvt_pk_bf16_f32 v248, v122, v123
	v_cvt_pk_bf16_f32 v249, v124, v125
	global_store_dwordx4 v251, v[246:249], s[26:27]
	v_mul_f32_e32 v96, v119, v133
	v_mul_f32_e32 v250, v119, v132
	v_mul_f32_e32 v130, v118, v132
	v_fma_f32 v119, v118, v133, v250
	v_sub_f32_e32 v118, v130, v96
	v_mul_f32_e32 v96, v121, v135
	v_mul_f32_e32 v250, v121, v134
	v_fma_f32 v121, v120, v135, v250
	v_fma_f32 v120, v120, v134, -v96
	v_mul_f32_e32 v96, v115, v137
	v_mul_f32_e32 v250, v115, v136
	v_mul_f32_e32 v130, v114, v136
	v_fma_f32 v115, v114, v137, v250
	v_sub_f32_e32 v114, v130, v96
	v_mul_f32_e32 v96, v117, v139
	v_mul_f32_e32 v250, v117, v138
	v_fma_f32 v117, v116, v139, v250
	v_fma_f32 v116, v116, v138, -v96
	v_cvt_pk_bf16_f32 v246, v118, v119
	v_cvt_pk_bf16_f32 v247, v120, v121
	v_cvt_pk_bf16_f32 v248, v114, v115
	v_cvt_pk_bf16_f32 v249, v116, v117
	global_store_dwordx4 v251, v[246:249], s[26:27] offset:256
	s_nop 1
	v_add_u32_e32 v251, s8, v251
	s_waitcnt vmcnt(14)
	v_mul_f32_e32 v96, v111, v141
	v_mul_f32_e32 v250, v111, v140
	v_mul_f32_e32 v130, v110, v140
	v_fma_f32 v111, v110, v141, v250
	v_sub_f32_e32 v110, v130, v96
	v_mul_f32_e32 v96, v113, v143
	v_mul_f32_e32 v250, v113, v142
	v_fma_f32 v113, v112, v143, v250
	v_fma_f32 v112, v112, v142, -v96
	v_mul_f32_e32 v96, v107, v149
	v_mul_f32_e32 v250, v107, v148
	v_mul_f32_e32 v130, v106, v148
	v_fma_f32 v107, v106, v149, v250
	v_sub_f32_e32 v106, v130, v96
	v_mul_f32_e32 v96, v109, v151
	v_mul_f32_e32 v250, v109, v150
	v_fma_f32 v109, v108, v151, v250
	v_fma_f32 v108, v108, v150, -v96
	v_cvt_pk_bf16_f32 v246, v110, v111
	v_cvt_pk_bf16_f32 v247, v112, v113
	v_cvt_pk_bf16_f32 v248, v106, v107
	v_cvt_pk_bf16_f32 v249, v108, v109
	global_store_dwordx4 v251, v[246:249], s[26:27]
	v_mul_f32_e32 v96, v103, v141
	v_mul_f32_e32 v250, v103, v140
	v_mul_f32_e32 v130, v102, v140
	v_fma_f32 v103, v102, v141, v250
	v_sub_f32_e32 v102, v130, v96
	v_mul_f32_e32 v96, v105, v143
	v_mul_f32_e32 v250, v105, v142
	v_fma_f32 v105, v104, v143, v250
	v_fma_f32 v104, v104, v142, -v96
	v_mul_f32_e32 v96, v99, v149
	v_mul_f32_e32 v250, v99, v148
	v_mul_f32_e32 v130, v98, v148
	v_fma_f32 v99, v98, v149, v250
	v_sub_f32_e32 v98, v130, v96
	v_mul_f32_e32 v96, v101, v151
	v_mul_f32_e32 v250, v101, v150
	v_fma_f32 v101, v100, v151, v250
	v_fma_f32 v100, v100, v150, -v96
	v_cvt_pk_bf16_f32 v246, v102, v103
	v_cvt_pk_bf16_f32 v247, v104, v105
	v_cvt_pk_bf16_f32 v248, v98, v99
	v_cvt_pk_bf16_f32 v249, v100, v101
	global_store_dwordx4 v251, v[246:249], s[26:27] offset:256
	s_nop 1
	v_add_u32_e32 v251, s8, v251
	s_waitcnt vmcnt(14)
; __device__ __forceinline__ unsigned cvt_pk_bf16(float lo, float hi) { unsigned r; asm volatile("v_cvt_pk_bf16_f32 %0, %1, %2" : "=v"(r) : "v"(lo), "v"(hi)); return r; }
;     __device__ __forceinline__ void operator()(const f32x4 (&acc)[2][2][4][2], const Unit& u, int wr, int wc, int fr, int fq) const {
;     ...
;                 const int row = row0 + ai * HALF + m * 16;
;                 bf16_t* rowp = O + (size_t)row * ldc + col0;
;                 f32x4 cs0 = {1.f, 0.f, 1.f, 0.f}, cs1 = {1.f, 0.f, 1.f, 0.f};
;                 if (mode == 1) {
;                     const int L1 = (1 << log2L) - 1, line = row >> log2L, uu = row & L1, rho = line & ((1 << log2d) - 1), pos = (uu << log2d) + rho;
;                     const float* tp = rope + ((size_t)pos * 32 + (wc & 1) * 16 + 4 * fq) * 2;
;                     cs0 = *(const f32x4*)tp; cs1 = *(const f32x4*)(tp + 4);
;                 }
; #pragma unroll
;                 for (int bj = 0; bj < 2; ++bj) {
;                     f32x4 v0 = acc[ai][bj][m][0], v1 = acc[ai][bj][m][1];
;                     if (mode == 2) {
; #pragma unroll
;                         for (int e = 0; e < 4; ++e) { float a = fmaxf(v0[e], 0.f), b = fmaxf(v1[e], 0.f); v0[e] = a * a; v1[e] = b * b; }
;                     } else if (mode == 1) {
;                         f32x4 r0, r1;
;                         r0[0] = v0[0] * cs0[0] - v0[1] * cs0[1]; r0[1] = v0[0] * cs0[1] + v0[1] * cs0[0];
;                         r0[2] = v0[2] * cs0[2] - v0[3] * cs0[3]; r0[3] = v0[2] * cs0[3] + v0[3] * cs0[2];
;                         r1[0] = v1[0] * cs1[0] - v1[1] * cs1[1]; r1[1] = v1[0] * cs1[1] + v1[1] * cs1[0];
;                         r1[2] = v1[2] * cs1[2] - v1[3] * cs1[3]; r1[3] = v1[2] * cs1[3] + v1[3] * cs1[2];
;                         v0 = r0; v1 = r1;
;                     }
;                     u32x4 w; w.x = cvt_pk_bf16(v0[0], v0[1]); w.y = cvt_pk_bf16(v0[2], v0[3]); w.z = cvt_pk_bf16(v1[0], v1[1]); w.w = cvt_pk_bf16(v1[2], v1[3]);
;                     *(u32x4*)(rowp + bj * HALF) = w;
	v_mul_f32_e32 v96, v93, v169
	v_mul_f32_e32 v250, v93, v168
	v_mul_f32_e32 v130, v92, v168
	v_fma_f32 v93, v92, v169, v250
	v_sub_f32_e32 v92, v130, v96
	v_mul_f32_e32 v96, v95, v171
	v_mul_f32_e32 v250, v95, v170
	v_fma_f32 v95, v94, v171, v250
	v_fma_f32 v94, v94, v170, -v96
	v_mul_f32_e32 v96, v89, v173
	v_mul_f32_e32 v250, v89, v172
	v_mul_f32_e32 v130, v88, v172
	v_fma_f32 v89, v88, v173, v250
	v_sub_f32_e32 v88, v130, v96
	v_mul_f32_e32 v96, v91, v175
	v_mul_f32_e32 v250, v91, v174
	v_fma_f32 v91, v90, v175, v250
	v_fma_f32 v90, v90, v174, -v96
	v_cvt_pk_bf16_f32 v246, v92, v93
	v_cvt_pk_bf16_f32 v247, v94, v95
	v_cvt_pk_bf16_f32 v248, v88, v89
	v_cvt_pk_bf16_f32 v249, v90, v91
	global_store_dwordx4 v251, v[246:249], s[26:27]
	v_mul_f32_e32 v96, v85, v169
	v_mul_f32_e32 v250, v85, v168
	v_mul_f32_e32 v130, v84, v168
	v_fma_f32 v85, v84, v169, v250
	v_sub_f32_e32 v84, v130, v96
	v_mul_f32_e32 v96, v87, v171
	v_mul_f32_e32 v250, v87, v170
	v_fma_f32 v87, v86, v171, v250
	v_fma_f32 v86, v86, v170, -v96
	v_mul_f32_e32 v96, v81, v173
	v_mul_f32_e32 v250, v81, v172
	v_mul_f32_e32 v130, v80, v172
	v_fma_f32 v81, v80, v173, v250
	v_sub_f32_e32 v80, v130, v96
	v_mul_f32_e32 v96, v83, v175
	v_mul_f32_e32 v250, v83, v174
	v_fma_f32 v83, v82, v175, v250
	v_fma_f32 v82, v82, v174, -v96
	v_cvt_pk_bf16_f32 v246, v84, v85
	v_cvt_pk_bf16_f32 v247, v86, v87
	v_cvt_pk_bf16_f32 v248, v80, v81
	v_cvt_pk_bf16_f32 v249, v82, v83
	global_store_dwordx4 v251, v[246:249], s[26:27] offset:256
	s_nop 1
	v_add_u32_e32 v251, s8, v251
	s_waitcnt vmcnt(14)
	v_mul_f32_e32 v96, v77, v177
	v_mul_f32_e32 v250, v77, v176
	v_mul_f32_e32 v130, v76, v176
	v_fma_f32 v77, v76, v177, v250
	v_sub_f32_e32 v76, v130, v96
	v_mul_f32_e32 v96, v79, v179
	v_mul_f32_e32 v250, v79, v178
	v_fma_f32 v79, v78, v179, v250
	v_fma_f32 v78, v78, v178, -v96
	v_mul_f32_e32 v96, v73, v211
	v_mul_f32_e32 v250, v73, v210
	v_mul_f32_e32 v130, v72, v210
	v_fma_f32 v73, v72, v211, v250
	v_sub_f32_e32 v72, v130, v96
	v_mul_f32_e32 v96, v75, v213
	v_mul_f32_e32 v250, v75, v212
	v_fma_f32 v75, v74, v213, v250
	v_fma_f32 v74, v74, v212, -v96
	v_cvt_pk_bf16_f32 v246, v76, v77
	v_cvt_pk_bf16_f32 v247, v78, v79
	v_cvt_pk_bf16_f32 v248, v72, v73
	v_cvt_pk_bf16_f32 v249, v74, v75
	global_store_dwordx4 v251, v[246:249], s[26:27]
	v_mul_f32_e32 v96, v69, v177
	v_mul_f32_e32 v250, v69, v176
	v_mul_f32_e32 v130, v68, v176
	v_fma_f32 v69, v68, v177, v250
	v_sub_f32_e32 v68, v130, v96
	v_mul_f32_e32 v96, v71, v179
	v_mul_f32_e32 v250, v71, v178
	v_fma_f32 v71, v70, v179, v250
	v_fma_f32 v70, v70, v178, -v96
	v_mul_f32_e32 v96, v65, v211
	v_mul_f32_e32 v250, v65, v210
	v_mul_f32_e32 v130, v64, v210
	v_fma_f32 v65, v64, v211, v250
	v_sub_f32_e32 v64, v130, v96
	v_mul_f32_e32 v96, v67, v213
	v_mul_f32_e32 v250, v67, v212
	v_fma_f32 v67, v66, v213, v250
	v_fma_f32 v66, v66, v212, -v96
	v_cvt_pk_bf16_f32 v246, v68, v69
	v_cvt_pk_bf16_f32 v247, v70, v71
	v_cvt_pk_bf16_f32 v248, v64, v65
	v_cvt_pk_bf16_f32 v249, v66, v67
	global_store_dwordx4 v251, v[246:249], s[26:27] offset:256
	s_nop 1
	v_add_u32_e32 v251, s9, v251
	s_waitcnt vmcnt(14)
	v_mul_f32_e32 v96, v61, v215
	v_mul_f32_e32 v250, v61, v214
	v_mul_f32_e32 v130, v60, v214
	v_fma_f32 v61, v60, v215, v250
	v_sub_f32_e32 v60, v130, v96
	v_mul_f32_e32 v96, v63, v217
	v_mul_f32_e32 v250, v63, v216
	v_fma_f32 v63, v62, v217, v250
	v_fma_f32 v62, v62, v216, -v96
	v_mul_f32_e32 v96, v57, v219
	v_mul_f32_e32 v250, v57, v218
	v_mul_f32_e32 v130, v56, v218
	v_fma_f32 v57, v56, v219, v250
	v_sub_f32_e32 v56, v130, v96
	v_mul_f32_e32 v96, v59, v221
	v_mul_f32_e32 v250, v59, v220
	v_fma_f32 v59, v58, v221, v250
	v_fma_f32 v58, v58, v220, -v96
	v_cvt_pk_bf16_f32 v246, v60, v61
	v_cvt_pk_bf16_f32 v247, v62, v63
	v_cvt_pk_bf16_f32 v248, v56, v57
	v_cvt_pk_bf16_f32 v249, v58, v59
	global_store_dwordx4 v251, v[246:249], s[26:27]
	v_mul_f32_e32 v96, v53, v215
	v_mul_f32_e32 v250, v53, v214
	v_mul_f32_e32 v130, v52, v214
	v_fma_f32 v53, v52, v215, v250
	v_sub_f32_e32 v52, v130, v96
	v_mul_f32_e32 v96, v55, v217
	v_mul_f32_e32 v250, v55, v216
	v_fma_f32 v55, v54, v217, v250
	v_fma_f32 v54, v54, v216, -v96
	v_mul_f32_e32 v96, v49, v219
	v_mul_f32_e32 v250, v49, v218
	v_mul_f32_e32 v130, v48, v218
	v_fma_f32 v49, v48, v219, v250
	v_sub_f32_e32 v48, v130, v96
	v_mul_f32_e32 v96, v51, v221
	v_mul_f32_e32 v250, v51, v220
	v_fma_f32 v51, v50, v221, v250
	v_fma_f32 v50, v50, v220, -v96
	v_cvt_pk_bf16_f32 v246, v52, v53
	v_cvt_pk_bf16_f32 v247, v54, v55
	v_cvt_pk_bf16_f32 v248, v48, v49
	v_cvt_pk_bf16_f32 v249, v50, v51
	global_store_dwordx4 v251, v[246:249], s[26:27] offset:256
	s_nop 1
	v_add_u32_e32 v251, s8, v251
	s_waitcnt vmcnt(14)
; __device__ __forceinline__ unsigned cvt_pk_bf16(float lo, float hi) { unsigned r; asm volatile("v_cvt_pk_bf16_f32 %0, %1, %2" : "=v"(r) : "v"(lo), "v"(hi)); return r; }
;     __device__ __forceinline__ void operator()(const f32x4 (&acc)[2][2][4][2], const Unit& u, int wr, int wc, int fr, int fq) const {
;     ...
;                 const int row = row0 + ai * HALF + m * 16;
;                 bf16_t* rowp = O + (size_t)row * ldc + col0;
;                 f32x4 cs0 = {1.f, 0.f, 1.f, 0.f}, cs1 = {1.f, 0.f, 1.f, 0.f};
;                 if (mode == 1) {
;                     const int L1 = (1 << log2L) - 1, line = row >> log2L, uu = row & L1, rho = line & ((1 << log2d) - 1), pos = (uu << log2d) + rho;
;                     const float* tp = rope + ((size_t)pos * 32 + (wc & 1) * 16 + 4 * fq) * 2;
;                     cs0 = *(const f32x4*)tp; cs1 = *(const f32x4*)(tp + 4);
;                 }
; #pragma unroll
;                 for (int bj = 0; bj < 2; ++bj) {
;                     f32x4 v0 = acc[ai][bj][m][0], v1 = acc[ai][bj][m][1];
;                     if (mode == 2) {
; #pragma unroll
;                         for (int e = 0; e < 4; ++e) { float a = fmaxf(v0[e], 0.f), b = fmaxf(v1[e], 0.f); v0[e] = a * a; v1[e] = b * b; }
;                     } else if (mode == 1) {
;                         f32x4 r0, r1;
;                         r0[0] = v0[0] * cs0[0] - v0[1] * cs0[1]; r0[1] = v0[0] * cs0[1] + v0[1] * cs0[0];
;                         r0[2] = v0[2] * cs0[2] - v0[3] * cs0[3]; r0[3] = v0[2] * cs0[3] + v0[3] * cs0[2];
;                         r1[0] = v1[0] * cs1[0] - v1[1] * cs1[1]; r1[1] = v1[0] * cs1[1] + v1[1] * cs1[0];
;                         r1[2] = v1[2] * cs1[2] - v1[3] * cs1[3]; r1[3] = v1[2] * cs1[3] + v1[3] * cs1[2];
;                         v0 = r0; v1 = r1;
;                     }
;                     u32x4 w; w.x = cvt_pk_bf16(v0[0], v0[1]); w.y = cvt_pk_bf16(v0[2], v0[3]); w.z = cvt_pk_bf16(v1[0], v1[1]); w.w = cvt_pk_bf16(v1[2], v1[3]);
;                     *(u32x4*)(rowp + bj * HALF) = w;
	v_mul_f32_e32 v96, v45, v223
	v_mul_f32_e32 v250, v45, v222
	v_mul_f32_e32 v130, v44, v222
	v_fma_f32 v45, v44, v223, v250
	v_sub_f32_e32 v44, v130, v96
	v_mul_f32_e32 v96, v47, v225
	v_mul_f32_e32 v250, v47, v224
	v_fma_f32 v47, v46, v225, v250
	v_fma_f32 v46, v46, v224, -v96
	v_mul_f32_e32 v96, v41, v227
	v_mul_f32_e32 v250, v41, v226
	v_mul_f32_e32 v130, v40, v226
	v_fma_f32 v41, v40, v227, v250
	v_sub_f32_e32 v40, v130, v96
	v_mul_f32_e32 v96, v43, v229
	v_mul_f32_e32 v250, v43, v228
	v_fma_f32 v43, v42, v229, v250
	v_fma_f32 v42, v42, v228, -v96
	v_cvt_pk_bf16_f32 v246, v44, v45
	v_cvt_pk_bf16_f32 v247, v46, v47
	v_cvt_pk_bf16_f32 v248, v40, v41
	v_cvt_pk_bf16_f32 v249, v42, v43
	global_store_dwordx4 v251, v[246:249], s[26:27]
	v_mul_f32_e32 v96, v37, v223
	v_mul_f32_e32 v250, v37, v222
	v_mul_f32_e32 v130, v36, v222
	v_fma_f32 v37, v36, v223, v250
	v_sub_f32_e32 v36, v130, v96
	v_mul_f32_e32 v96, v39, v225
	v_mul_f32_e32 v250, v39, v224
	v_fma_f32 v39, v38, v225, v250
	v_fma_f32 v38, v38, v224, -v96
	v_mul_f32_e32 v96, v33, v227
	v_mul_f32_e32 v250, v33, v226
	v_mul_f32_e32 v130, v32, v226
	v_fma_f32 v33, v32, v227, v250
	v_sub_f32_e32 v32, v130, v96
	v_mul_f32_e32 v96, v35, v229
	v_mul_f32_e32 v250, v35, v228
	v_fma_f32 v35, v34, v229, v250
	v_fma_f32 v34, v34, v228, -v96
	v_cvt_pk_bf16_f32 v246, v36, v37
	v_cvt_pk_bf16_f32 v247, v38, v39
	v_cvt_pk_bf16_f32 v248, v32, v33
	v_cvt_pk_bf16_f32 v249, v34, v35
	global_store_dwordx4 v251, v[246:249], s[26:27] offset:256
	s_nop 1
	v_add_u32_e32 v251, s8, v251
	s_waitcnt vmcnt(14)
	v_mul_f32_e32 v96, v29, v231
	v_mul_f32_e32 v250, v29, v230
	v_mul_f32_e32 v130, v28, v230
	v_fma_f32 v29, v28, v231, v250
	v_sub_f32_e32 v28, v130, v96
	v_mul_f32_e32 v96, v31, v233
	v_mul_f32_e32 v250, v31, v232
	v_fma_f32 v31, v30, v233, v250
	v_fma_f32 v30, v30, v232, -v96
	v_mul_f32_e32 v96, v25, v235
	v_mul_f32_e32 v250, v25, v234
	v_mul_f32_e32 v130, v24, v234
	v_fma_f32 v25, v24, v235, v250
	v_sub_f32_e32 v24, v130, v96
	v_mul_f32_e32 v96, v27, v237
	v_mul_f32_e32 v250, v27, v236
	v_fma_f32 v27, v26, v237, v250
	v_fma_f32 v26, v26, v236, -v96
	v_cvt_pk_bf16_f32 v246, v28, v29
	v_cvt_pk_bf16_f32 v247, v30, v31
	v_cvt_pk_bf16_f32 v248, v24, v25
	v_cvt_pk_bf16_f32 v249, v26, v27
	global_store_dwordx4 v251, v[246:249], s[26:27]
	v_mul_f32_e32 v96, v21, v231
	v_mul_f32_e32 v250, v21, v230
	v_mul_f32_e32 v130, v20, v230
	v_fma_f32 v21, v20, v231, v250
	v_sub_f32_e32 v20, v130, v96
	v_mul_f32_e32 v96, v23, v233
	v_mul_f32_e32 v250, v23, v232
	v_fma_f32 v23, v22, v233, v250
	v_fma_f32 v22, v22, v232, -v96
	v_mul_f32_e32 v96, v17, v235
	v_mul_f32_e32 v250, v17, v234
	v_mul_f32_e32 v130, v16, v234
	v_fma_f32 v17, v16, v235, v250
	v_sub_f32_e32 v16, v130, v96
	v_mul_f32_e32 v96, v19, v237
	v_mul_f32_e32 v250, v19, v236
	v_fma_f32 v19, v18, v237, v250
	v_fma_f32 v18, v18, v236, -v96
	v_cvt_pk_bf16_f32 v246, v20, v21
	v_cvt_pk_bf16_f32 v247, v22, v23
	v_cvt_pk_bf16_f32 v248, v16, v17
	v_cvt_pk_bf16_f32 v249, v18, v19
	global_store_dwordx4 v251, v[246:249], s[26:27] offset:256
	s_nop 1
	v_add_u32_e32 v251, s8, v251
	s_waitcnt vmcnt(14)
	v_mul_f32_e32 v96, v13, v239
	v_mul_f32_e32 v250, v13, v238
	v_mul_f32_e32 v130, v12, v238
	v_fma_f32 v13, v12, v239, v250
	v_sub_f32_e32 v12, v130, v96
	v_mul_f32_e32 v96, v15, v241
	v_mul_f32_e32 v250, v15, v240
	v_fma_f32 v15, v14, v241, v250
	v_fma_f32 v14, v14, v240, -v96
	v_mul_f32_e32 v96, v9, v243
	v_mul_f32_e32 v250, v9, v242
	v_mul_f32_e32 v130, v8, v242
	v_fma_f32 v9, v8, v243, v250
	v_sub_f32_e32 v8, v130, v96
	v_mul_f32_e32 v96, v11, v245
	v_mul_f32_e32 v250, v11, v244
	v_fma_f32 v11, v10, v245, v250
	v_fma_f32 v10, v10, v244, -v96
	v_cvt_pk_bf16_f32 v246, v12, v13
	v_cvt_pk_bf16_f32 v247, v14, v15
	v_cvt_pk_bf16_f32 v248, v8, v9
	v_cvt_pk_bf16_f32 v249, v10, v11
	global_store_dwordx4 v251, v[246:249], s[26:27]
	v_mul_f32_e32 v96, v5, v239
	v_mul_f32_e32 v250, v5, v238
	v_mul_f32_e32 v130, v4, v238
	v_fma_f32 v5, v4, v239, v250
	v_sub_f32_e32 v4, v130, v96
	v_mul_f32_e32 v96, v7, v241
	v_mul_f32_e32 v250, v7, v240
	v_fma_f32 v7, v6, v241, v250
	v_fma_f32 v6, v6, v240, -v96
	v_mul_f32_e32 v96, v1, v243
	v_mul_f32_e32 v250, v1, v242
	v_mul_f32_e32 v130, v0, v242
	v_fma_f32 v1, v0, v243, v250
	v_sub_f32_e32 v0, v130, v96
	v_mul_f32_e32 v96, v3, v245
	v_mul_f32_e32 v250, v3, v244
	v_fma_f32 v3, v2, v245, v250
	v_fma_f32 v2, v2, v244, -v96
	v_cvt_pk_bf16_f32 v246, v4, v5
	v_cvt_pk_bf16_f32 v247, v6, v7
	v_cvt_pk_bf16_f32 v248, v0, v1
	v_cvt_pk_bf16_f32 v249, v2, v3
	global_store_dwordx4 v251, v[246:249], s[26:27] offset:256
	s_branch .LBB0_256
